# v24 attention LDS prefetch plus GEMM epilogue stores (PROJ/HID/XB) without the nt hint so the next phase can find them in the memory-side cache
# speedup vs baseline: 1.0056x; 1.0056x over previous
; __device__ __forceinline__ unsigned cvt_pk_bf16(float lo, float hi) { const f32x2_t v = {lo, hi}; const bf16x2_t b = __builtin_convertvector(v, bf16x2_t); return __builtin_bit_cast(unsigned, b); }
;     __device__ __forceinline__ void operator()(const f32x4 (&acc)[2][2][4][2], const Unit& u, int wr, int wc, int fr, int fq) const {
;         const int row0 = u.pm * BM + wr * 64 + fr; const int col0 = u.pn * BM + wc * 32 + 8 * fq;
; #pragma unroll
;         for (int ai = 0; ai < 2; ++ai)
; #pragma unroll
;             for (int m = 0; m < 4; ++m) { bf16_t* rowp = O + (size_t)(row0 + ai * HALF + m * 16) * ldc + col0;
; #pragma unroll
;                 for (int bj = 0; bj < 2; ++bj) { const f32x4 v0 = acc[ai][bj][m][0], v1 = acc[ai][bj][m][1];
;                     u32x4 w; w.x = cvt_pk_bf16(v0[0], v0[1]); w.y = cvt_pk_bf16(v0[2], v0[3]); w.z = cvt_pk_bf16(v1[0], v1[1]); w.w = cvt_pk_bf16(v1[2], v1[3]);
;                     __builtin_nontemporal_store(w, (u32x4*)(rowp + bj * HALF)); } }
;     }
.LBB0_357:
	v_readlane_b32 s56, v255, 26
	v_lshl_add_u32 v150, s66, 8, v140
	v_lshl_or_b32 v144, s65, 8, v142
	v_readlane_b32 s57, v255, 27
	v_ashrrev_i32_e32 v145, 31, v144
	v_cvt_pk_bf16_f32 v70, v70, v71
	v_mov_b64_e32 v[146:147], s[56:57]
	v_cvt_pk_bf16_f32 v71, v72, v73
	v_cvt_pk_bf16_f32 v72, v66, v67
	v_add_u32_e32 v66, 0x80, v150
	v_mad_i64_i32 v[148:149], s[52:53], v150, s28, v[146:147]
	v_lshlrev_b64 v[144:145], 1, v[144:145]
	v_cvt_pk_bf16_f32 v110, v110, v111
	v_cvt_pk_bf16_f32 v111, v112, v113
	v_cvt_pk_bf16_f32 v112, v106, v107
	v_or_b32_e32 v106, 16, v150
	v_mad_i64_i32 v[66:67], s[52:53], v66, s28, v[146:147]
	v_cvt_pk_bf16_f32 v46, v46, v47
	v_cvt_pk_bf16_f32 v47, v48, v49
	v_cvt_pk_bf16_f32 v48, v42, v43
	v_add_u32_e32 v42, 0x90, v150
	v_lshl_add_u64 v[148:149], v[148:149], 0, v[144:145]
	v_cvt_pk_bf16_f32 v113, v108, v109
	v_mad_i64_i32 v[106:107], s[52:53], v106, s28, v[146:147]
	v_cvt_pk_bf16_f32 v94, v94, v95
	v_cvt_pk_bf16_f32 v95, v96, v97
	v_cvt_pk_bf16_f32 v96, v90, v91
	v_or_b32_e32 v90, 32, v150
	v_lshl_add_u64 v[66:67], v[66:67], 0, v[144:145]
	v_cvt_pk_bf16_f32 v49, v44, v45
	v_mad_i64_i32 v[42:43], s[52:53], v42, s28, v[146:147]
	v_cvt_pk_bf16_f32 v30, v30, v31
	v_cvt_pk_bf16_f32 v31, v32, v33
	v_cvt_pk_bf16_f32 v32, v26, v27
	v_add_u32_e32 v26, 0xa0, v150
	global_store_dwordx4 v[148:149], v[110:113], off offset:256
	v_cvt_pk_bf16_f32 v97, v92, v93
	v_mad_i64_i32 v[90:91], s[52:53], v90, s28, v[146:147]
	v_lshl_add_u64 v[110:111], v[106:107], 0, v[144:145]
	v_cvt_pk_bf16_f32 v78, v78, v79
	v_cvt_pk_bf16_f32 v79, v80, v81
	v_cvt_pk_bf16_f32 v80, v74, v75
	v_or_b32_e32 v74, 48, v150
	global_store_dwordx4 v[66:67], v[46:49], off offset:256
	v_cvt_pk_bf16_f32 v33, v28, v29
	v_mad_i64_i32 v[26:27], s[52:53], v26, s28, v[146:147]
	v_lshl_add_u64 v[46:47], v[42:43], 0, v[144:145]
	v_cvt_pk_bf16_f32 v14, v14, v15
	v_cvt_pk_bf16_f32 v15, v16, v17
	v_cvt_pk_bf16_f32 v16, v10, v11
	v_add_u32_e32 v10, 0xb0, v150
	global_store_dwordx4 v[110:111], v[94:97], off offset:256
	v_cvt_pk_bf16_f32 v81, v76, v77
	v_mad_i64_i32 v[74:75], s[52:53], v74, s28, v[146:147]
	v_lshl_add_u64 v[94:95], v[90:91], 0, v[144:145]
	global_store_dwordx4 v[46:47], v[30:33], off offset:256
	v_cvt_pk_bf16_f32 v17, v12, v13
	v_mad_i64_i32 v[10:11], s[52:53], v10, s28, v[146:147]
	v_lshl_add_u64 v[30:31], v[26:27], 0, v[144:145]
	v_cvt_pk_bf16_f32 v126, v126, v127
	v_cvt_pk_bf16_f32 v127, v128, v129
	v_cvt_pk_bf16_f32 v128, v122, v123
	v_cvt_pk_bf16_f32 v129, v124, v125
	v_cvt_pk_bf16_f32 v106, v118, v119
	v_cvt_pk_bf16_f32 v107, v120, v121
	v_cvt_pk_bf16_f32 v108, v114, v115
	v_cvt_pk_bf16_f32 v109, v116, v117
	v_cvt_pk_bf16_f32 v90, v102, v103
	v_cvt_pk_bf16_f32 v91, v104, v105
	v_cvt_pk_bf16_f32 v92, v98, v99
	v_cvt_pk_bf16_f32 v93, v100, v101
	global_store_dwordx4 v[94:95], v[78:81], off offset:256
	v_cvt_pk_bf16_f32 v76, v82, v83
	v_cvt_pk_bf16_f32 v77, v84, v85
	v_lshl_add_u64 v[78:79], v[74:75], 0, v[144:145]
	v_cvt_pk_bf16_f32 v74, v86, v87
	v_cvt_pk_bf16_f32 v75, v88, v89
	v_cvt_pk_bf16_f32 v73, v68, v69
	v_cvt_pk_bf16_f32 v62, v62, v63
	v_cvt_pk_bf16_f32 v63, v64, v65
	v_cvt_pk_bf16_f32 v64, v58, v59
	v_cvt_pk_bf16_f32 v65, v60, v61
	v_cvt_pk_bf16_f32 v42, v54, v55
	v_cvt_pk_bf16_f32 v43, v56, v57
	v_cvt_pk_bf16_f32 v44, v50, v51
	v_cvt_pk_bf16_f32 v45, v52, v53
	v_cvt_pk_bf16_f32 v26, v38, v39
	v_cvt_pk_bf16_f32 v27, v40, v41
	v_cvt_pk_bf16_f32 v28, v34, v35
	v_cvt_pk_bf16_f32 v29, v36, v37
	global_store_dwordx4 v[30:31], v[14:17], off offset:256
	v_cvt_pk_bf16_f32 v12, v18, v19
	v_cvt_pk_bf16_f32 v13, v20, v21
	v_lshl_add_u64 v[14:15], v[10:11], 0, v[144:145]
	v_cvt_pk_bf16_f32 v10, v22, v23
	v_cvt_pk_bf16_f32 v11, v24, v25
	v_cvt_pk_bf16_f32 v6, v6, v7
	v_cvt_pk_bf16_f32 v7, v8, v9
	v_cvt_pk_bf16_f32 v8, v2, v3
	v_cvt_pk_bf16_f32 v9, v4, v5
	s_andn2_b64 vcc, exec, s[40:41]
	s_mov_b64 s[40:41], -1
	v_readlane_b32 s70, v255, 24
	s_mov_b32 s76, s79
	global_store_dwordx4 v[148:149], v[126:129], off
	global_store_dwordx4 v[110:111], v[106:109], off
	global_store_dwordx4 v[94:95], v[90:93], off
	global_store_dwordx4 v[78:79], v[74:77], off
	global_store_dwordx4 v[78:79], v[70:73], off offset:256
	global_store_dwordx4 v[66:67], v[62:65], off
	global_store_dwordx4 v[46:47], v[42:45], off
	global_store_dwordx4 v[30:31], v[26:29], off
	global_store_dwordx4 v[14:15], v[10:13], off
	global_store_dwordx4 v[14:15], v[6:9], off offset:256
	v_readlane_b32 s71, v255, 25
	s_cbranch_vccnz .LBB0_350
	s_andn2_b64 vcc, exec, s[20:21]
	s_cbranch_vccnz .LBB0_349
	s_barrier
	s_branch .LBB0_349

; __device__ __forceinline__ unsigned cvt_pk_bf16(float lo, float hi) { const f32x2_t v = {lo, hi}; const bf16x2_t b = __builtin_convertvector(v, bf16x2_t); return __builtin_bit_cast(unsigned, b); }
; __device__ __forceinline__ float silu_f(float g) { return g * __builtin_amdgcn_rcpf(1.0f + __expf(-g)); }
;     __device__ __forceinline__ void operator()(const f32x4 (&acc)[2][2][4][2], const Unit& u, int wr, int wc, int fr, int fq) const {
;         const int row0 = u.pm * BM + wr * 64 + fr; const int col0 = u.pn * HALF + wc * 32 + 8 * fq;
; #pragma unroll
;         for (int ai = 0; ai < 2; ++ai)
; #pragma unroll
;             for (int m = 0; m < 4; ++m) { bf16_t* rowp = O + (size_t)(row0 + ai * HALF + m * 16) * ldc + col0;
;                 const f32x4 g0 = acc[ai][0][m][0], g1 = acc[ai][0][m][1], u0 = acc[ai][1][m][0], u1 = acc[ai][1][m][1];
;                 u32x4 w; w.x = cvt_pk_bf16(silu_f(g0[0]) * u0[0], silu_f(g0[1]) * u0[1]); w.y = cvt_pk_bf16(silu_f(g0[2]) * u0[2], silu_f(g0[3]) * u0[3]);
;                 w.z = cvt_pk_bf16(silu_f(g1[0]) * u1[0], silu_f(g1[1]) * u1[1]); w.w = cvt_pk_bf16(silu_f(g1[2]) * u1[2], silu_f(g1[3]) * u1[3]);
;                 __builtin_nontemporal_store(w, (u32x4*)rowp); asm volatile("" ::: "memory"); }
.LBB0_1092:
	v_mul_f32_e32 v149, 0xbfb8aa3b, v126
	v_exp_f32_e32 v149, v149
	v_lshl_or_b32 v142, s33, 7, v146
	v_lshl_add_u32 v148, s48, 8, v144
	v_ashrrev_i32_e32 v143, 31, v142
	v_add_f32_e32 v149, 1.0, v149
	v_rcp_f32_e32 v152, v149
	v_mul_f32_e32 v149, 0xbfb8aa3b, v127
	v_exp_f32_e32 v149, v149
	v_mov_b64_e32 v[140:141], s[80:81]
	v_mad_i64_i32 v[150:151], s[20:21], v148, s29, v[140:141]
	v_add_f32_e32 v149, 1.0, v149
	v_rcp_f32_e32 v153, v149
	v_lshlrev_b64 v[142:143], 1, v[142:143]
	v_lshl_add_u64 v[150:151], v[150:151], 0, v[142:143]
	s_andn2_b64 vcc, exec, s[40:41]
	v_pk_mul_f32 v[126:127], v[126:127], v[152:153]
	s_nop 0
	v_pk_mul_f32 v[122:123], v[126:127], v[122:123]
	s_nop 0
	v_cvt_pk_bf16_f32 v122, v122, v123
	v_mul_f32_e32 v123, 0xbfb8aa3b, v128
	v_exp_f32_e32 v123, v123
	s_nop 0
	v_add_f32_e32 v123, 1.0, v123
	v_rcp_f32_e32 v126, v123
	v_mul_f32_e32 v123, 0xbfb8aa3b, v129
	v_exp_f32_e32 v123, v123
	s_nop 0
	v_add_f32_e32 v123, 1.0, v123
	v_rcp_f32_e32 v127, v123
	s_nop 0
	v_pk_mul_f32 v[126:127], v[128:129], v[126:127]
	s_nop 0
	v_pk_mul_f32 v[124:125], v[126:127], v[124:125]
	s_nop 0
	v_cvt_pk_bf16_f32 v123, v124, v125
	v_mul_f32_e32 v124, 0xbfb8aa3b, v118
	v_mul_f32_e32 v125, 0xbfb8aa3b, v119
	v_exp_f32_e32 v124, v124
	v_exp_f32_e32 v125, v125
	v_add_f32_e32 v124, 1.0, v124
	v_add_f32_e32 v125, 1.0, v125
	v_rcp_f32_e32 v124, v124
	v_rcp_f32_e32 v125, v125
	s_nop 0
	v_pk_mul_f32 v[118:119], v[118:119], v[124:125]
	s_nop 0
	v_pk_mul_f32 v[114:115], v[118:119], v[114:115]
	s_nop 0
	v_cvt_pk_bf16_f32 v124, v114, v115
	v_mul_f32_e32 v114, 0xbfb8aa3b, v120
	v_mul_f32_e32 v115, 0xbfb8aa3b, v121
	v_exp_f32_e32 v114, v114
	v_exp_f32_e32 v115, v115
	v_add_f32_e32 v114, 1.0, v114
	v_add_f32_e32 v115, 1.0, v115
	v_rcp_f32_e32 v114, v114
	v_rcp_f32_e32 v115, v115
	s_nop 0
	v_pk_mul_f32 v[114:115], v[120:121], v[114:115]
	s_nop 0
	v_pk_mul_f32 v[114:115], v[114:115], v[116:117]
	v_mul_f32_e32 v116, 0xbfb8aa3b, v110
	v_mul_f32_e32 v117, 0xbfb8aa3b, v111
	v_exp_f32_e32 v116, v116
	v_exp_f32_e32 v117, v117
	v_cvt_pk_bf16_f32 v125, v114, v115
	v_or_b32_e32 v114, 16, v148
	v_add_f32_e32 v116, 1.0, v116
	v_add_f32_e32 v117, 1.0, v117
	v_rcp_f32_e32 v116, v116
	v_rcp_f32_e32 v117, v117
	v_mad_i64_i32 v[114:115], s[20:21], v114, s29, v[140:141]
	global_store_dwordx4 v[150:151], v[122:125], off
	v_pk_mul_f32 v[110:111], v[110:111], v[116:117]
	v_lshl_add_u64 v[114:115], v[114:115], 0, v[142:143]
	v_pk_mul_f32 v[106:107], v[110:111], v[106:107]
	s_nop 0
	v_cvt_pk_bf16_f32 v106, v106, v107
	v_mul_f32_e32 v107, 0xbfb8aa3b, v112
	v_exp_f32_e32 v107, v107
	s_nop 0
	v_add_f32_e32 v107, 1.0, v107
	v_rcp_f32_e32 v110, v107
	v_mul_f32_e32 v107, 0xbfb8aa3b, v113
	v_exp_f32_e32 v107, v107
	s_nop 0
	v_add_f32_e32 v107, 1.0, v107
	v_rcp_f32_e32 v111, v107
	s_nop 0
	v_pk_mul_f32 v[110:111], v[112:113], v[110:111]
	s_nop 0
	v_pk_mul_f32 v[108:109], v[110:111], v[108:109]
	s_nop 0
	v_cvt_pk_bf16_f32 v107, v108, v109
	v_mul_f32_e32 v108, 0xbfb8aa3b, v102
	v_mul_f32_e32 v109, 0xbfb8aa3b, v103
	v_exp_f32_e32 v108, v108
	v_exp_f32_e32 v109, v109
	v_add_f32_e32 v108, 1.0, v108
	v_add_f32_e32 v109, 1.0, v109
	v_rcp_f32_e32 v108, v108
	v_rcp_f32_e32 v109, v109
	s_nop 0
	v_pk_mul_f32 v[102:103], v[102:103], v[108:109]
	s_nop 0
	v_pk_mul_f32 v[98:99], v[102:103], v[98:99]
	s_nop 0
	v_cvt_pk_bf16_f32 v108, v98, v99
	v_mul_f32_e32 v98, 0xbfb8aa3b, v104
	v_mul_f32_e32 v99, 0xbfb8aa3b, v105
	v_exp_f32_e32 v98, v98
	v_exp_f32_e32 v99, v99
	v_add_f32_e32 v98, 1.0, v98
	v_add_f32_e32 v99, 1.0, v99
	v_rcp_f32_e32 v98, v98
	v_rcp_f32_e32 v99, v99
	s_nop 0
	v_pk_mul_f32 v[98:99], v[104:105], v[98:99]
	s_nop 0
	v_pk_mul_f32 v[98:99], v[98:99], v[100:101]
	v_mul_f32_e32 v100, 0xbfb8aa3b, v94
	v_mul_f32_e32 v101, 0xbfb8aa3b, v95
	v_exp_f32_e32 v100, v100
	v_exp_f32_e32 v101, v101
	v_cvt_pk_bf16_f32 v109, v98, v99
	v_or_b32_e32 v98, 32, v148
	v_add_f32_e32 v100, 1.0, v100
	v_add_f32_e32 v101, 1.0, v101
	v_rcp_f32_e32 v100, v100
	v_rcp_f32_e32 v101, v101
	v_mad_i64_i32 v[98:99], s[20:21], v98, s29, v[140:141]
	global_store_dwordx4 v[114:115], v[106:109], off
	v_pk_mul_f32 v[94:95], v[94:95], v[100:101]
	v_lshl_add_u64 v[98:99], v[98:99], 0, v[142:143]
	v_pk_mul_f32 v[90:91], v[94:95], v[90:91]
	s_nop 0
	v_cvt_pk_bf16_f32 v90, v90, v91
	v_mul_f32_e32 v91, 0xbfb8aa3b, v96
	v_exp_f32_e32 v91, v91
	s_nop 0
	v_add_f32_e32 v91, 1.0, v91
	v_rcp_f32_e32 v94, v91
	v_mul_f32_e32 v91, 0xbfb8aa3b, v97
	v_exp_f32_e32 v91, v91
	s_nop 0
	v_add_f32_e32 v91, 1.0, v91
	v_rcp_f32_e32 v95, v91
	s_nop 0
	v_pk_mul_f32 v[94:95], v[96:97], v[94:95]
	s_nop 0
	v_pk_mul_f32 v[92:93], v[94:95], v[92:93]
	s_nop 0
	v_cvt_pk_bf16_f32 v91, v92, v93
	v_mul_f32_e32 v92, 0xbfb8aa3b, v86
	v_mul_f32_e32 v93, 0xbfb8aa3b, v87
	v_exp_f32_e32 v92, v92
	v_exp_f32_e32 v93, v93
	v_add_f32_e32 v92, 1.0, v92
	v_add_f32_e32 v93, 1.0, v93
	v_rcp_f32_e32 v92, v92
	v_rcp_f32_e32 v93, v93
	s_nop 0
	v_pk_mul_f32 v[86:87], v[86:87], v[92:93]
	s_nop 0
	v_pk_mul_f32 v[82:83], v[86:87], v[82:83]
	s_nop 0
	v_cvt_pk_bf16_f32 v92, v82, v83
	v_mul_f32_e32 v82, 0xbfb8aa3b, v88
	v_mul_f32_e32 v83, 0xbfb8aa3b, v89
	v_exp_f32_e32 v82, v82
	v_exp_f32_e32 v83, v83
	v_add_f32_e32 v82, 1.0, v82
	v_add_f32_e32 v83, 1.0, v83
	v_rcp_f32_e32 v82, v82
	v_rcp_f32_e32 v83, v83
	s_nop 0
	v_pk_mul_f32 v[82:83], v[88:89], v[82:83]
	s_nop 0
	v_pk_mul_f32 v[82:83], v[82:83], v[84:85]
	v_mul_f32_e32 v84, 0xbfb8aa3b, v78
	v_mul_f32_e32 v85, 0xbfb8aa3b, v79
	v_exp_f32_e32 v84, v84
	v_exp_f32_e32 v85, v85
	v_cvt_pk_bf16_f32 v93, v82, v83
	v_or_b32_e32 v82, 48, v148
	v_add_f32_e32 v84, 1.0, v84
	v_add_f32_e32 v85, 1.0, v85
	v_rcp_f32_e32 v84, v84
	v_rcp_f32_e32 v85, v85
; __device__ __forceinline__ unsigned cvt_pk_bf16(float lo, float hi) { const f32x2_t v = {lo, hi}; const bf16x2_t b = __builtin_convertvector(v, bf16x2_t); return __builtin_bit_cast(unsigned, b); }
; __device__ __forceinline__ float silu_f(float g) { return g * __builtin_amdgcn_rcpf(1.0f + __expf(-g)); }
;     __device__ __forceinline__ void operator()(const f32x4 (&acc)[2][2][4][2], const Unit& u, int wr, int wc, int fr, int fq) const {
;     ...
;             for (int m = 0; m < 4; ++m) { bf16_t* rowp = O + (size_t)(row0 + ai * HALF + m * 16) * ldc + col0;
;                 const f32x4 g0 = acc[ai][0][m][0], g1 = acc[ai][0][m][1], u0 = acc[ai][1][m][0], u1 = acc[ai][1][m][1];
;                 u32x4 w; w.x = cvt_pk_bf16(silu_f(g0[0]) * u0[0], silu_f(g0[1]) * u0[1]); w.y = cvt_pk_bf16(silu_f(g0[2]) * u0[2], silu_f(g0[3]) * u0[3]);
;                 w.z = cvt_pk_bf16(silu_f(g1[0]) * u1[0], silu_f(g1[1]) * u1[1]); w.w = cvt_pk_bf16(silu_f(g1[2]) * u1[2], silu_f(g1[3]) * u1[3]);
;                 __builtin_nontemporal_store(w, (u32x4*)rowp); asm volatile("" ::: "memory"); }
	v_mad_i64_i32 v[82:83], s[20:21], v82, s29, v[140:141]
	global_store_dwordx4 v[98:99], v[90:93], off
	v_pk_mul_f32 v[78:79], v[78:79], v[84:85]
	v_lshl_add_u64 v[82:83], v[82:83], 0, v[142:143]
	v_pk_mul_f32 v[74:75], v[78:79], v[74:75]
	s_nop 0
	v_cvt_pk_bf16_f32 v74, v74, v75
	v_mul_f32_e32 v75, 0xbfb8aa3b, v80
	v_exp_f32_e32 v75, v75
	s_nop 0
	v_add_f32_e32 v75, 1.0, v75
	v_rcp_f32_e32 v78, v75
	v_mul_f32_e32 v75, 0xbfb8aa3b, v81
	v_exp_f32_e32 v75, v75
	s_nop 0
	v_add_f32_e32 v75, 1.0, v75
	v_rcp_f32_e32 v79, v75
	s_nop 0
	v_pk_mul_f32 v[78:79], v[80:81], v[78:79]
	s_nop 0
	v_pk_mul_f32 v[76:77], v[78:79], v[76:77]
	s_nop 0
	v_cvt_pk_bf16_f32 v75, v76, v77
	v_mul_f32_e32 v76, 0xbfb8aa3b, v70
	v_mul_f32_e32 v77, 0xbfb8aa3b, v71
	v_exp_f32_e32 v76, v76
	v_exp_f32_e32 v77, v77
	v_add_f32_e32 v76, 1.0, v76
	v_add_f32_e32 v77, 1.0, v77
	v_rcp_f32_e32 v76, v76
	v_rcp_f32_e32 v77, v77
	s_nop 0
	v_pk_mul_f32 v[70:71], v[70:71], v[76:77]
	s_nop 0
	v_pk_mul_f32 v[66:67], v[70:71], v[66:67]
	s_nop 0
	v_cvt_pk_bf16_f32 v76, v66, v67
	v_mul_f32_e32 v66, 0xbfb8aa3b, v72
	v_mul_f32_e32 v67, 0xbfb8aa3b, v73
	v_exp_f32_e32 v66, v66
	v_exp_f32_e32 v67, v67
	v_add_f32_e32 v66, 1.0, v66
	v_add_f32_e32 v67, 1.0, v67
	v_rcp_f32_e32 v66, v66
	v_rcp_f32_e32 v67, v67
	s_nop 0
	v_pk_mul_f32 v[66:67], v[72:73], v[66:67]
	s_nop 0
	v_pk_mul_f32 v[66:67], v[66:67], v[68:69]
	v_mul_f32_e32 v68, 0xbfb8aa3b, v62
	v_mul_f32_e32 v69, 0xbfb8aa3b, v63
	v_exp_f32_e32 v68, v68
	v_exp_f32_e32 v69, v69
	v_cvt_pk_bf16_f32 v77, v66, v67
	v_add_u32_e32 v66, 0x80, v148
	v_add_f32_e32 v68, 1.0, v68
	v_add_f32_e32 v69, 1.0, v69
	v_rcp_f32_e32 v68, v68
	v_rcp_f32_e32 v69, v69
	v_mad_i64_i32 v[66:67], s[20:21], v66, s29, v[140:141]
	global_store_dwordx4 v[82:83], v[74:77], off
	v_pk_mul_f32 v[62:63], v[62:63], v[68:69]
	v_lshl_add_u64 v[66:67], v[66:67], 0, v[142:143]
	v_pk_mul_f32 v[58:59], v[62:63], v[58:59]
	s_nop 0
	v_cvt_pk_bf16_f32 v58, v58, v59
	v_mul_f32_e32 v59, 0xbfb8aa3b, v64
	v_exp_f32_e32 v59, v59
	s_nop 0
	v_add_f32_e32 v59, 1.0, v59
	v_rcp_f32_e32 v62, v59
	v_mul_f32_e32 v59, 0xbfb8aa3b, v65
	v_exp_f32_e32 v59, v59
	s_nop 0
	v_add_f32_e32 v59, 1.0, v59
	v_rcp_f32_e32 v63, v59
	s_nop 0
	v_pk_mul_f32 v[62:63], v[64:65], v[62:63]
	s_nop 0
	v_pk_mul_f32 v[60:61], v[62:63], v[60:61]
	s_nop 0
	v_cvt_pk_bf16_f32 v59, v60, v61
	v_mul_f32_e32 v60, 0xbfb8aa3b, v54
	v_mul_f32_e32 v61, 0xbfb8aa3b, v55
	v_exp_f32_e32 v60, v60
	v_exp_f32_e32 v61, v61
	v_add_f32_e32 v60, 1.0, v60
	v_add_f32_e32 v61, 1.0, v61
	v_rcp_f32_e32 v60, v60
	v_rcp_f32_e32 v61, v61
	s_nop 0
	v_pk_mul_f32 v[54:55], v[54:55], v[60:61]
	s_nop 0
	v_pk_mul_f32 v[50:51], v[54:55], v[50:51]
	s_nop 0
	v_cvt_pk_bf16_f32 v60, v50, v51
	v_mul_f32_e32 v50, 0xbfb8aa3b, v56
	v_mul_f32_e32 v51, 0xbfb8aa3b, v57
	v_exp_f32_e32 v50, v50
	v_exp_f32_e32 v51, v51
	v_add_f32_e32 v50, 1.0, v50
	v_add_f32_e32 v51, 1.0, v51
	v_rcp_f32_e32 v50, v50
	v_rcp_f32_e32 v51, v51
	s_nop 0
	v_pk_mul_f32 v[50:51], v[56:57], v[50:51]
	s_nop 0
	v_pk_mul_f32 v[50:51], v[50:51], v[52:53]
	v_mul_f32_e32 v52, 0xbfb8aa3b, v46
	v_mul_f32_e32 v53, 0xbfb8aa3b, v47
	v_exp_f32_e32 v52, v52
	v_exp_f32_e32 v53, v53
	v_cvt_pk_bf16_f32 v61, v50, v51
	v_add_u32_e32 v50, 0x90, v148
	v_add_f32_e32 v52, 1.0, v52
	v_add_f32_e32 v53, 1.0, v53
	v_rcp_f32_e32 v52, v52
	v_rcp_f32_e32 v53, v53
	v_mad_i64_i32 v[50:51], s[20:21], v50, s29, v[140:141]
	global_store_dwordx4 v[66:67], v[58:61], off
	v_pk_mul_f32 v[46:47], v[46:47], v[52:53]
	v_lshl_add_u64 v[50:51], v[50:51], 0, v[142:143]
	v_pk_mul_f32 v[42:43], v[46:47], v[42:43]
	s_nop 0
	v_cvt_pk_bf16_f32 v42, v42, v43
	v_mul_f32_e32 v43, 0xbfb8aa3b, v48
	v_exp_f32_e32 v43, v43
	s_nop 0
	v_add_f32_e32 v43, 1.0, v43
	v_rcp_f32_e32 v46, v43
	v_mul_f32_e32 v43, 0xbfb8aa3b, v49
	v_exp_f32_e32 v43, v43
	s_nop 0
	v_add_f32_e32 v43, 1.0, v43
	v_rcp_f32_e32 v47, v43
	s_nop 0
	v_pk_mul_f32 v[46:47], v[48:49], v[46:47]
	s_nop 0
	v_pk_mul_f32 v[44:45], v[46:47], v[44:45]
	s_nop 0
	v_cvt_pk_bf16_f32 v43, v44, v45
	v_mul_f32_e32 v44, 0xbfb8aa3b, v38
	v_mul_f32_e32 v45, 0xbfb8aa3b, v39
	v_exp_f32_e32 v44, v44
; __device__ __forceinline__ unsigned cvt_pk_bf16(float lo, float hi) { const f32x2_t v = {lo, hi}; const bf16x2_t b = __builtin_convertvector(v, bf16x2_t); return __builtin_bit_cast(unsigned, b); }
; __device__ __forceinline__ float silu_f(float g) { return g * __builtin_amdgcn_rcpf(1.0f + __expf(-g)); }
;     __device__ __forceinline__ void operator()(const f32x4 (&acc)[2][2][4][2], const Unit& u, int wr, int wc, int fr, int fq) const {
;     ...
;             for (int m = 0; m < 4; ++m) { bf16_t* rowp = O + (size_t)(row0 + ai * HALF + m * 16) * ldc + col0;
;                 const f32x4 g0 = acc[ai][0][m][0], g1 = acc[ai][0][m][1], u0 = acc[ai][1][m][0], u1 = acc[ai][1][m][1];
;                 u32x4 w; w.x = cvt_pk_bf16(silu_f(g0[0]) * u0[0], silu_f(g0[1]) * u0[1]); w.y = cvt_pk_bf16(silu_f(g0[2]) * u0[2], silu_f(g0[3]) * u0[3]);
;                 w.z = cvt_pk_bf16(silu_f(g1[0]) * u1[0], silu_f(g1[1]) * u1[1]); w.w = cvt_pk_bf16(silu_f(g1[2]) * u1[2], silu_f(g1[3]) * u1[3]);
;                 __builtin_nontemporal_store(w, (u32x4*)rowp); asm volatile("" ::: "memory"); }
;     }
	v_exp_f32_e32 v45, v45
	v_add_f32_e32 v44, 1.0, v44
	v_add_f32_e32 v45, 1.0, v45
	v_rcp_f32_e32 v44, v44
	v_rcp_f32_e32 v45, v45
	s_nop 0
	v_pk_mul_f32 v[38:39], v[38:39], v[44:45]
	s_nop 0
	v_pk_mul_f32 v[34:35], v[38:39], v[34:35]
	s_nop 0
	v_cvt_pk_bf16_f32 v44, v34, v35
	v_mul_f32_e32 v34, 0xbfb8aa3b, v40
	v_mul_f32_e32 v35, 0xbfb8aa3b, v41
	v_exp_f32_e32 v34, v34
	v_exp_f32_e32 v35, v35
	v_add_f32_e32 v34, 1.0, v34
	v_add_f32_e32 v35, 1.0, v35
	v_rcp_f32_e32 v34, v34
	v_rcp_f32_e32 v35, v35
	s_nop 0
	v_pk_mul_f32 v[34:35], v[40:41], v[34:35]
	s_nop 0
	v_pk_mul_f32 v[34:35], v[34:35], v[36:37]
	v_mul_f32_e32 v36, 0xbfb8aa3b, v30
	v_mul_f32_e32 v37, 0xbfb8aa3b, v31
	v_exp_f32_e32 v36, v36
	v_exp_f32_e32 v37, v37
	v_cvt_pk_bf16_f32 v45, v34, v35
	v_add_u32_e32 v34, 0xa0, v148
	v_add_f32_e32 v36, 1.0, v36
	v_add_f32_e32 v37, 1.0, v37
	v_rcp_f32_e32 v36, v36
	v_rcp_f32_e32 v37, v37
	v_mad_i64_i32 v[34:35], s[20:21], v34, s29, v[140:141]
	global_store_dwordx4 v[50:51], v[42:45], off
	v_pk_mul_f32 v[30:31], v[30:31], v[36:37]
	v_lshl_add_u64 v[34:35], v[34:35], 0, v[142:143]
	v_pk_mul_f32 v[26:27], v[30:31], v[26:27]
	s_nop 0
	v_cvt_pk_bf16_f32 v26, v26, v27
	v_mul_f32_e32 v27, 0xbfb8aa3b, v32
	v_exp_f32_e32 v27, v27
	s_nop 0
	v_add_f32_e32 v27, 1.0, v27
	v_rcp_f32_e32 v30, v27
	v_mul_f32_e32 v27, 0xbfb8aa3b, v33
	v_exp_f32_e32 v27, v27
	s_nop 0
	v_add_f32_e32 v27, 1.0, v27
	v_rcp_f32_e32 v31, v27
	s_nop 0
	v_pk_mul_f32 v[30:31], v[32:33], v[30:31]
	s_nop 0
	v_pk_mul_f32 v[28:29], v[30:31], v[28:29]
	s_nop 0
	v_cvt_pk_bf16_f32 v27, v28, v29
	v_mul_f32_e32 v28, 0xbfb8aa3b, v22
	v_mul_f32_e32 v29, 0xbfb8aa3b, v23
	v_exp_f32_e32 v28, v28
	v_exp_f32_e32 v29, v29
	v_add_f32_e32 v28, 1.0, v28
	v_add_f32_e32 v29, 1.0, v29
	v_rcp_f32_e32 v28, v28
	v_rcp_f32_e32 v29, v29
	s_nop 0
	v_pk_mul_f32 v[22:23], v[22:23], v[28:29]
	s_nop 0
	v_pk_mul_f32 v[18:19], v[22:23], v[18:19]
	s_nop 0
	v_cvt_pk_bf16_f32 v28, v18, v19
	v_mul_f32_e32 v18, 0xbfb8aa3b, v24
	v_mul_f32_e32 v19, 0xbfb8aa3b, v25
	v_exp_f32_e32 v18, v18
	v_exp_f32_e32 v19, v19
	v_add_f32_e32 v18, 1.0, v18
	v_add_f32_e32 v19, 1.0, v19
	v_rcp_f32_e32 v18, v18
	v_rcp_f32_e32 v19, v19
	s_nop 0
	v_pk_mul_f32 v[18:19], v[24:25], v[18:19]
	s_nop 0
	v_pk_mul_f32 v[18:19], v[18:19], v[20:21]
	v_mul_f32_e32 v20, 0xbfb8aa3b, v14
	v_mul_f32_e32 v21, 0xbfb8aa3b, v15
	v_exp_f32_e32 v20, v20
	v_exp_f32_e32 v21, v21
	v_cvt_pk_bf16_f32 v29, v18, v19
	v_add_u32_e32 v18, 0xb0, v148
	v_add_f32_e32 v20, 1.0, v20
	v_add_f32_e32 v21, 1.0, v21
	v_rcp_f32_e32 v20, v20
	v_rcp_f32_e32 v21, v21
	v_mad_i64_i32 v[18:19], s[20:21], v18, s29, v[140:141]
	global_store_dwordx4 v[34:35], v[26:29], off
	v_pk_mul_f32 v[14:15], v[14:15], v[20:21]
	v_lshl_add_u64 v[18:19], v[18:19], 0, v[142:143]
	v_pk_mul_f32 v[10:11], v[14:15], v[10:11]
	s_mov_b64 s[20:21], -1
	v_cvt_pk_bf16_f32 v10, v10, v11
	v_mul_f32_e32 v11, 0xbfb8aa3b, v16
	v_exp_f32_e32 v11, v11
	s_nop 0
	v_add_f32_e32 v11, 1.0, v11
	v_rcp_f32_e32 v14, v11
	v_mul_f32_e32 v11, 0xbfb8aa3b, v17
	v_exp_f32_e32 v11, v11
	s_nop 0
	v_add_f32_e32 v11, 1.0, v11
	v_rcp_f32_e32 v15, v11
	s_nop 0
	v_pk_mul_f32 v[14:15], v[16:17], v[14:15]
	s_nop 0
	v_pk_mul_f32 v[12:13], v[14:15], v[12:13]
	s_nop 0
	v_cvt_pk_bf16_f32 v11, v12, v13
	v_mul_f32_e32 v12, 0xbfb8aa3b, v6
	v_mul_f32_e32 v13, 0xbfb8aa3b, v7
	v_exp_f32_e32 v12, v12
	v_exp_f32_e32 v13, v13
	v_add_f32_e32 v12, 1.0, v12
	v_add_f32_e32 v13, 1.0, v13
	v_rcp_f32_e32 v12, v12
	v_rcp_f32_e32 v13, v13
	s_nop 0
	v_pk_mul_f32 v[6:7], v[6:7], v[12:13]
	s_nop 0
	v_pk_mul_f32 v[2:3], v[6:7], v[2:3]
	s_nop 0
	v_cvt_pk_bf16_f32 v12, v2, v3
	v_mul_f32_e32 v2, 0xbfb8aa3b, v8
	v_mul_f32_e32 v3, 0xbfb8aa3b, v9
	v_exp_f32_e32 v2, v2
	v_exp_f32_e32 v3, v3
	v_add_f32_e32 v2, 1.0, v2
	v_add_f32_e32 v3, 1.0, v3
	v_rcp_f32_e32 v2, v2
	v_rcp_f32_e32 v3, v3
	s_nop 0
	v_pk_mul_f32 v[2:3], v[8:9], v[2:3]
	s_nop 0
	v_pk_mul_f32 v[2:3], v[2:3], v[4:5]
	s_nop 0
	v_cvt_pk_bf16_f32 v13, v2, v3
	global_store_dwordx4 v[18:19], v[10:13], off
	s_cbranch_vccnz .LBB0_1085
	s_andn2_b64 vcc, exec, s[0:1]
	s_cbranch_vccnz .LBB0_1084
	s_barrier
	s_branch .LBB0_1084

; __device__ __forceinline__ unsigned cvt_pk_bf16(float lo, float hi) { const f32x2_t v = {lo, hi}; const bf16x2_t b = __builtin_convertvector(v, bf16x2_t); return __builtin_bit_cast(unsigned, b); }
;     __device__ __forceinline__ void operator()(const f32x4 (&acc)[2][2][4][2], const Unit& u, int wr, int wc, int fr, int fq) const {
;     ...
;         } else { bf16_t* xo = (bf16_t*)Xout;
; #pragma unroll
;             for (int ai = 0; ai < 2; ++ai)
; #pragma unroll
;                 for (int m = 0; m < 4; ++m)
; #pragma unroll
;                     for (int bj = 0; bj < 2; ++bj) { const f32x4 v0 = acc[ai][bj][m][0], v1 = acc[ai][bj][m][1];
;                         u32x4 w; w.x = cvt_pk_bf16(v0[0], v0[1]); w.y = cvt_pk_bf16(v0[2], v0[3]); w.z = cvt_pk_bf16(v1[0], v1[1]); w.w = cvt_pk_bf16(v1[2], v1[3]);
;                         __builtin_nontemporal_store(w, (u32x4*)(xo + (size_t)(row0 + ai * HALF + m * 16) * ldc + col0 + bj * HALF)); }
.LBB0_1188:
	v_lshl_add_u32 v144, s49, 8, v150
	v_lshl_or_b32 v146, s79, 8, v152
	v_ashrrev_i32_e32 v147, 31, v146
	v_ashrrev_i32_e32 v145, 31, v144
	s_mov_b64 s[52:53], -1
	s_and_b64 vcc, exec, s[56:57]
	v_or_b32_e32 v148, 16, v144
	v_or_b32_e32 v142, 32, v144
	v_or_b32_e32 v140, 48, v144
	s_cbranch_vccz .LBB0_1190
	v_lshl_add_u64 v[158:159], v[146:147], 1, s[86:87]
	v_lshlrev_b64 v[160:161], 12, v[144:145]
	v_cvt_pk_bf16_f32 v154, v2, v3
	v_cvt_pk_bf16_f32 v155, v4, v5
	v_cvt_pk_bf16_f32 v156, v6, v7
	v_cvt_pk_bf16_f32 v157, v8, v9
	v_lshl_add_u64 v[160:161], v[158:159], 0, v[160:161]
	v_ashrrev_i32_e32 v149, 31, v148
	global_store_dwordx4 v[160:161], v[154:157], off
	v_lshlrev_b64 v[162:163], 12, v[148:149]
	v_lshl_add_u64 v[162:163], v[158:159], 0, v[162:163]
	v_cvt_pk_bf16_f32 v154, v18, v19
	v_cvt_pk_bf16_f32 v155, v20, v21
	v_cvt_pk_bf16_f32 v156, v22, v23
	v_cvt_pk_bf16_f32 v157, v24, v25
	global_store_dwordx4 v[160:161], v[154:157], off offset:256
	v_ashrrev_i32_e32 v143, 31, v142
	v_ashrrev_i32_e32 v141, 31, v140
	v_cvt_pk_bf16_f32 v154, v10, v11
	v_cvt_pk_bf16_f32 v155, v12, v13
	v_cvt_pk_bf16_f32 v156, v14, v15
	v_cvt_pk_bf16_f32 v157, v16, v17
	global_store_dwordx4 v[162:163], v[154:157], off
	s_mov_b32 s25, 0x80000
	s_nop 0
	v_cvt_pk_bf16_f32 v154, v34, v35
	v_cvt_pk_bf16_f32 v155, v36, v37
	v_cvt_pk_bf16_f32 v156, v38, v39
	v_cvt_pk_bf16_f32 v157, v40, v41
	global_store_dwordx4 v[162:163], v[154:157], off offset:256
	v_lshlrev_b64 v[162:163], 12, v[142:143]
	v_lshl_add_u64 v[162:163], v[158:159], 0, v[162:163]
	v_cvt_pk_bf16_f32 v154, v26, v27
	v_cvt_pk_bf16_f32 v155, v28, v29
	v_cvt_pk_bf16_f32 v156, v30, v31
	v_cvt_pk_bf16_f32 v157, v32, v33
	global_store_dwordx4 v[162:163], v[154:157], off
	s_nop 1
	v_cvt_pk_bf16_f32 v154, v50, v51
	v_cvt_pk_bf16_f32 v155, v52, v53
	v_cvt_pk_bf16_f32 v156, v54, v55
	v_cvt_pk_bf16_f32 v157, v56, v57
	global_store_dwordx4 v[162:163], v[154:157], off offset:256
	v_lshlrev_b64 v[162:163], 12, v[140:141]
	v_lshl_add_u64 v[158:159], v[158:159], 0, v[162:163]
	v_cvt_pk_bf16_f32 v154, v42, v43
	v_cvt_pk_bf16_f32 v155, v44, v45
	v_cvt_pk_bf16_f32 v156, v46, v47
	v_cvt_pk_bf16_f32 v157, v48, v49
	global_store_dwordx4 v[158:159], v[154:157], off
	v_add_co_u32_e32 v162, vcc, s25, v160
	s_nop 0
	v_cvt_pk_bf16_f32 v154, v58, v59
	v_cvt_pk_bf16_f32 v155, v60, v61
	v_cvt_pk_bf16_f32 v156, v66, v67
	v_cvt_pk_bf16_f32 v157, v68, v69
	global_store_dwordx4 v[158:159], v[154:157], off offset:256
	v_addc_co_u32_e32 v163, vcc, 0, v161, vcc
	s_nop 0
	v_cvt_pk_bf16_f32 v154, v62, v63
	v_cvt_pk_bf16_f32 v155, v64, v65
	v_cvt_pk_bf16_f32 v156, v70, v71
	v_cvt_pk_bf16_f32 v157, v72, v73
	s_mov_b32 s25, 0x90000
	v_lshl_add_u64 v[158:159], v[160:161], 0, s[58:59]
	global_store_dwordx4 v[162:163], v[154:157], off
	v_add_co_u32_e32 v162, vcc, s25, v160
	s_nop 0
	v_cvt_pk_bf16_f32 v154, v78, v79
	v_cvt_pk_bf16_f32 v155, v80, v81
	v_cvt_pk_bf16_f32 v156, v82, v83
	v_cvt_pk_bf16_f32 v157, v84, v85
	global_store_dwordx4 v[158:159], v[154:157], off offset:256
	v_addc_co_u32_e32 v163, vcc, 0, v161, vcc
	s_nop 0
	v_cvt_pk_bf16_f32 v154, v74, v75
	v_cvt_pk_bf16_f32 v155, v76, v77
	v_cvt_pk_bf16_f32 v156, v86, v87
	v_cvt_pk_bf16_f32 v157, v88, v89
	s_mov_b32 s25, 0xa0000
	v_lshl_add_u64 v[158:159], v[160:161], 0, s[14:15]
	global_store_dwordx4 v[162:163], v[154:157], off
	v_add_co_u32_e32 v162, vcc, s25, v160
	s_nop 0
	v_cvt_pk_bf16_f32 v154, v98, v99
	v_cvt_pk_bf16_f32 v155, v100, v101
	v_cvt_pk_bf16_f32 v156, v106, v107
	v_cvt_pk_bf16_f32 v157, v108, v109
	global_store_dwordx4 v[158:159], v[154:157], off offset:256
	v_addc_co_u32_e32 v163, vcc, 0, v161, vcc
	s_nop 0
	v_cvt_pk_bf16_f32 v154, v90, v91
	v_cvt_pk_bf16_f32 v155, v92, v93
	v_cvt_pk_bf16_f32 v156, v94, v95
	v_cvt_pk_bf16_f32 v157, v96, v97
	v_lshl_add_u64 v[158:159], v[160:161], 0, s[16:17]
	global_store_dwordx4 v[162:163], v[154:157], off
	s_mov_b32 s25, 0xb0000
	s_nop 0
	v_cvt_pk_bf16_f32 v154, v114, v115
	v_cvt_pk_bf16_f32 v155, v116, v117
	v_cvt_pk_bf16_f32 v156, v118, v119
	v_cvt_pk_bf16_f32 v157, v120, v121
	global_store_dwordx4 v[158:159], v[154:157], off offset:256
	v_lshl_add_u64 v[158:159], v[160:161], 0, s[18:19]
	v_add_co_u32_e32 v160, vcc, s25, v160
	v_cvt_pk_bf16_f32 v154, v102, v103
	v_cvt_pk_bf16_f32 v155, v104, v105
	v_cvt_pk_bf16_f32 v156, v110, v111
	v_cvt_pk_bf16_f32 v157, v112, v113
	v_addc_co_u32_e32 v161, vcc, 0, v161, vcc
	global_store_dwordx4 v[160:161], v[154:157], off
	s_nop 1
	v_cvt_pk_bf16_f32 v154, v122, v123
	v_cvt_pk_bf16_f32 v155, v124, v125
	v_cvt_pk_bf16_f32 v156, v126, v127
	v_cvt_pk_bf16_f32 v157, v128, v129
	global_store_dwordx4 v[158:159], v[154:157], off offset:256
	s_cbranch_execnz .LBB0_1192
	s_branch .LBB0_1191
